# EPI_RES GEMM instances (one block per CU): all 10 DMA pieces of the next stage issued right after the stage barrier; others keep 4
# speedup vs baseline: 1.0111x; 1.0111x over previous
; template <int EPI, int MI>
; DI void gemm_tile(const GemmDesc& g, int tm, int tn, char* smem) {
;     ...
;   const int tid = get_tid(), lane = tid & 63, wave = tid >> 6, r = lane & 31, hh = lane >> 5;
;   const int wm = wave >> 1, wn = wave & 1;
;   const int m0 = tm * BM, n0 = tn * 128;
;   const int nk = g.K >> 6;
;   f32x16 acc[MI][2];
; #pragma unroll
;   for (int a = 0; a < MI; ++a)
; #pragma unroll
;     for (int b = 0; b < 2; ++b)
; #pragma unroll
;       for (int i = 0; i < 16; ++i) acc[a][b][i] = 0.f;
;   const int srow = tid >> 3;
;   const int schunk = (tid & 7) ^ ((srow & 7) ^ ((srow >> 3) & 3));
;     ...
;   const int rowA = wm * (32 * MI) + r, rowB = wn * 64 + r;
;   const int hk = hh ^ ((r & 7) ^ ((r >> 3) & 3));
;     ...
;   G_GLDS(0, 0);
;   asm volatile("s_waitcnt vmcnt(0)" ::: "memory");
;   __syncthreads();
; template <int EPI, int MI>
; DI void gemm_phase(const GemmDesc& g, char* smem, int vb, int nvb) {
;     ...
;   for (int q = start; q < local; q += step) {
;     const int mg = q / per;
;     const int rem = q - mg * per;
;     const int tn = rem / PM;
;     const int tm = mbase + mg * PM + (rem - tn * PM);
.LBB0_254:
	s_abs_i32 s0, s42
	v_readlane_b32 s1, v219, 48
	s_mul_hi_u32 s1, s0, s1
	v_readlane_b32 s17, v219, 47
	s_mul_i32 s4, s1, s17
	s_sub_i32 s0, s0, s4
	s_ashr_i32 s15, s42, 31
	s_add_i32 s4, s1, 1
	s_sub_i32 s5, s0, s17
	s_cmp_ge_u32 s0, s17
	s_cselect_b32 s1, s4, s1
	s_cselect_b32 s0, s5, s0
	s_add_i32 s4, s1, 1
	s_cmp_ge_u32 s0, s17
	s_cselect_b32 s0, s4, s1
	s_xor_b32 s16, s0, s15
	s_sub_i32 s0, s16, s15
	s_mul_i32 s1, s0, s17
	s_sub_i32 s1, s42, s1
	s_abs_i32 s4, s1
	v_readlane_b32 s5, v219, 46
	s_mul_hi_u32 s5, s4, s5
	v_readlane_b32 s43, v218, 32
	s_mul_i32 s18, s5, s43
	s_sub_i32 s4, s4, s18
	s_ashr_i32 s17, s1, 31
	s_add_i32 s18, s5, 1
	s_sub_i32 s19, s4, s43
	s_cmp_ge_u32 s4, s43
	s_cselect_b32 s5, s18, s5
	s_cselect_b32 s4, s19, s4
	s_add_i32 s18, s5, 1
	s_cmp_ge_u32 s4, s43
	s_cselect_b32 s4, s18, s5
	s_xor_b32 s18, s4, s17
	v_mov_b32_e32 v97, v132
	s_sub_i32 s4, s18, s17
	s_mul_i32 s0, s0, s43
	v_ashrrev_i32_e32 v6, 3, v97
	s_mul_i32 s5, s4, s43
	s_waitcnt vmcnt(8)
	v_ashrrev_i32_e32 v109, 7, v97
	v_bfe_u32 v1, v97, 6, 2
	v_xor_b32_e32 v2, v6, v97
	s_add_i32 s0, s0, s54
	s_sub_i32 s1, s1, s5
	v_and_b32_e32 v108, 31, v97
	v_bitop3_b32 v2, v2, v1, 7 bitop3:0x6c
	v_mul_lo_u32 v1, v109, s6
	s_add_i32 s1, s0, s1
	s_lshl_b32 s0, s4, 7
	v_and_b32_e32 v0, 7, v97
	v_or_b32_e32 v7, v1, v108
	v_lshrrev_b32_e32 v1, 3, v97
	v_readlane_b32 s4, v221, 5
	s_mul_i32 s43, s1, 0xc0
	v_bfe_u32 v115, v97, 5, 1
	v_bitop3_b32 v0, v1, v0, 3 bitop3:0x6c
	v_readlane_b32 s5, v221, 6
	v_xor_b32_e32 v8, v0, v115
	v_add_u32_e32 v3, s43, v6
	v_mov_b64_e32 v[0:1], s[4:5]
	s_movk_i32 s19, 0x1600
	v_mad_i64_i32 v[0:1], s[4:5], v3, s19, v[0:1]
	v_readlane_b32 s4, v221, 10
	v_readlane_b32 s5, v221, 11
	v_lshlrev_b32_e32 v98, 4, v2
	v_add_u32_e32 v9, s0, v6
	v_mov_b64_e32 v[2:3], s[4:5]
	v_lshlrev_b32_e32 v120, 4, v97
	v_mad_i64_i32 v[2:3], s[4:5], v9, s19, v[2:3]
	v_add_u32_e32 v121, 0, v120
	v_mov_b32_e32 v99, v96
	v_readfirstlane_b32 s4, v121
	v_add_u32_e32 v122, 0x1000, v121
	v_lshl_add_u64 v[0:1], v[0:1], 0, v[98:99]
	s_mov_b32 m0, s4
	s_mov_b64 s[44:45], 0x2c000
	v_readfirstlane_b32 s4, v122
	v_add_u32_e32 v123, 0x2000, v121
	global_load_lds_dwordx4 v[0:1], off
	v_lshl_add_u64 v[4:5], v[0:1], 0, s[44:45]
	s_mov_b32 m0, s4
	s_mov_b64 s[46:47], 0x58000
	v_readfirstlane_b32 s4, v123
	v_add_u32_e32 v124, 0x3000, v121
	global_load_lds_dwordx4 v[4:5], off
	v_lshl_add_u64 v[4:5], v[0:1], 0, s[46:47]
	s_mov_b32 m0, s4
	s_mov_b64 s[52:53], 0x84000
	v_readfirstlane_b32 s4, v124
	global_load_lds_dwordx4 v[4:5], off
	v_lshl_add_u64 v[4:5], v[0:1], 0, s[52:53]
	s_mov_b32 m0, s4
	s_mov_b64 s[4:5], 0xb0000
	v_add_u32_e32 v125, 0x4000, v121
	global_load_lds_dwordx4 v[4:5], off
	v_lshl_add_u64 v[4:5], v[0:1], 0, s[4:5]
	v_readfirstlane_b32 s4, v125
	s_mov_b32 m0, s4
	s_mov_b64 s[4:5], 0xdc000
	v_add_u32_e32 v126, 0x5000, v121
	v_lshl_add_u64 v[0:1], v[0:1], 0, s[4:5]
	v_readfirstlane_b32 s4, v126
	v_add_u32_e32 v127, 0xc000, v121
	global_load_lds_dwordx4 v[4:5], off
	s_mov_b32 m0, s4
	v_readfirstlane_b32 s4, v127
	v_add_u32_e32 v128, 0xd000, v121
	global_load_lds_dwordx4 v[0:1], off
	v_lshl_add_u64 v[0:1], v[2:3], 0, v[98:99]
	s_mov_b32 m0, s4
	v_readfirstlane_b32 s4, v128
	v_add_u32_e32 v129, 0xe000, v121
	global_load_lds_dwordx4 v[0:1], off
	v_lshl_add_u64 v[2:3], v[0:1], 0, s[44:45]
	s_mov_b32 m0, s4
	v_readfirstlane_b32 s4, v129
	v_add_u32_e32 v130, 0xf000, v121
	global_load_lds_dwordx4 v[2:3], off
	v_lshl_add_u64 v[2:3], v[0:1], 0, s[46:47]
	s_mov_b32 m0, s4
	v_readfirstlane_b32 s4, v130
	global_load_lds_dwordx4 v[2:3], off
	v_lshl_add_u64 v[0:1], v[0:1], 0, s[52:53]
	s_mov_b32 m0, s4
	s_mul_i32 s15, s15, 7
	global_load_lds_dwordx4 v[0:1], off
	s_add_i32 s17, s17, s15
	s_sub_i32 s4, s17, s18
	s_mul_i32 s16, s16, 7
	s_sub_i32 s4, s4, s16
	v_readlane_b32 s5, v218, 33
	v_lshlrev_b32_e32 v0, 7, v97
	s_mul_i32 s4, s5, s4
	v_and_b32_e32 v0, 0x2f80, v0
	s_add_i32 s4, s4, s39
	s_waitcnt vmcnt(0)
	v_add_u32_e32 v153, 0, v0
	v_add_u32_e32 v155, s10, v0
	v_add_u32_e32 v2, s4, v6
	v_mov_b64_e32 v[0:1], s[70:71]
	v_lshlrev_b32_e32 v154, 4, v8
	v_mad_i64_i32 v[100:101], s[4:5], v2, s19, v[0:1]
	v_mad_i64_i32 v[102:103], s[4:5], v9, s19, v[0:1]
	v_mov_b32_e32 v0, 0
	v_lshl_add_u32 v131, v7, 7, 0
	v_xor_b32_e32 v156, 32, v154
	v_xor_b32_e32 v157, 64, v154
	v_xor_b32_e32 v158, 0x60, v154
	s_mov_b32 s15, 0
	v_mov_b32_e32 v1, v0
	v_mov_b32_e32 v2, v0
	v_mov_b32_e32 v3, v0
	v_mov_b32_e32 v4, v0
	v_mov_b32_e32 v5, v0
	v_mov_b32_e32 v6, v0
	v_mov_b32_e32 v7, v0
	v_mov_b32_e32 v8, v0
	v_mov_b32_e32 v9, v0
	v_mov_b32_e32 v10, v0
	v_mov_b32_e32 v11, v0
	v_mov_b32_e32 v12, v0
	v_mov_b32_e32 v13, v0
	v_mov_b32_e32 v14, v0
	v_mov_b32_e32 v15, v0
	v_mov_b32_e32 v16, v0
	v_mov_b32_e32 v17, v0
	v_mov_b32_e32 v18, v0
	v_mov_b32_e32 v19, v0
	v_mov_b32_e32 v20, v0
	v_mov_b32_e32 v21, v0
	v_mov_b32_e32 v22, v0
	v_mov_b32_e32 v23, v0
	v_mov_b32_e32 v24, v0
	v_mov_b32_e32 v25, v0
	v_mov_b32_e32 v26, v0
	v_mov_b32_e32 v27, v0
	v_mov_b32_e32 v28, v0
	v_mov_b32_e32 v29, v0
	v_mov_b32_e32 v30, v0
	v_mov_b32_e32 v31, v0
	v_mov_b32_e32 v32, v0
	v_mov_b32_e32 v33, v0
	v_mov_b32_e32 v34, v0
	v_mov_b32_e32 v35, v0
	v_mov_b32_e32 v36, v0
	v_mov_b32_e32 v37, v0
	v_mov_b32_e32 v38, v0
	v_mov_b32_e32 v39, v0
	v_mov_b32_e32 v40, v0
	v_mov_b32_e32 v41, v0
	v_mov_b32_e32 v42, v0
	v_mov_b32_e32 v43, v0
	v_mov_b32_e32 v44, v0
	v_mov_b32_e32 v45, v0
	v_mov_b32_e32 v46, v0
	v_mov_b32_e32 v47, v0
	v_mov_b32_e32 v48, v0
	s_waitcnt vmcnt(0)
; template <int EPI, int MI>
; DI void gemm_tile(const GemmDesc& g, int tm, int tn, char* smem) {
;     ...
; #pragma unroll
;   for (int a = 0; a < MI; ++a)
; #pragma unroll
;     for (int b = 0; b < 2; ++b)
; #pragma unroll
;       for (int i = 0; i < 16; ++i) acc[a][b][i] = 0.f;
;   const int srow = tid >> 3;
;   const int schunk = (tid & 7) ^ ((srow & 7) ^ ((srow >> 3) & 3));
;     ...
;   const int rowA = wm * (32 * MI) + r, rowB = wn * 64 + r;
;   const int hk = hh ^ ((r & 7) ^ ((r >> 3) & 3));
;     ...
;   G_GLDS(0, 0);
;   asm volatile("s_waitcnt vmcnt(0)" ::: "memory");
;   __syncthreads();
;   for (int kt = 0; kt < nk; kt += 2) {
;     if (kt + 1 < nk) G_GLDS(kt + 1, 1);
;     G_COMPUTE(0);
;     asm volatile("s_waitcnt vmcnt(0)" ::: "memory");
;     __syncthreads();
	v_mov_b32_e32 v49, v0
	v_mov_b32_e32 v50, v0
	v_mov_b32_e32 v51, v0
	v_mov_b32_e32 v52, v0
	v_mov_b32_e32 v53, v0
	v_mov_b32_e32 v54, v0
	v_mov_b32_e32 v55, v0
	v_mov_b32_e32 v56, v0
	v_mov_b32_e32 v57, v0
	v_mov_b32_e32 v58, v0
	v_mov_b32_e32 v59, v0
	v_mov_b32_e32 v60, v0
	v_mov_b32_e32 v61, v0
	v_mov_b32_e32 v62, v0
	v_mov_b32_e32 v63, v0
	v_mov_b32_e32 v64, v0
	v_mov_b32_e32 v65, v0
	v_mov_b32_e32 v66, v0
	v_mov_b32_e32 v67, v0
	v_mov_b32_e32 v68, v0
	v_mov_b32_e32 v69, v0
	v_mov_b32_e32 v70, v0
	v_mov_b32_e32 v71, v0
	v_mov_b32_e32 v72, v0
	v_mov_b32_e32 v73, v0
	v_mov_b32_e32 v74, v0
	v_mov_b32_e32 v75, v0
	v_mov_b32_e32 v76, v0
	v_mov_b32_e32 v77, v0
	v_mov_b32_e32 v78, v0
	v_mov_b32_e32 v79, v0
	v_mov_b32_e32 v80, v0
	v_mov_b32_e32 v81, v0
	v_mov_b32_e32 v82, v0
	v_mov_b32_e32 v83, v0
	v_mov_b32_e32 v84, v0
	v_mov_b32_e32 v85, v0
	v_mov_b32_e32 v86, v0
	v_mov_b32_e32 v87, v0
	v_mov_b32_e32 v88, v0
	v_mov_b32_e32 v89, v0
	v_mov_b32_e32 v90, v0
	v_mov_b32_e32 v91, v0
	v_mov_b32_e32 v92, v0
	v_mov_b32_e32 v93, v0
	v_mov_b32_e32 v94, v0
	v_mov_b32_e32 v95, v0
	v_add_u32_e32 v162, v131, v154
	v_add_u32_e32 v163, v131, v156
	v_add_u32_e32 v164, v131, v157
	v_add_u32_e32 v165, v131, v158
	v_add_u32_e32 v166, v153, v154
	v_add_u32_e32 v167, v153, v156
	v_add_u32_e32 v168, v153, v157
	v_add_u32_e32 v169, v153, v158
	v_add_u32_e32 v170, v155, v154
	v_add_u32_e32 v171, v155, v156
	v_add_u32_e32 v172, v155, v157
	v_add_u32_e32 v173, v155, v158
	v_lshl_add_u64 v[252:253], v[100:101], 0, v[98:99]
	v_lshl_add_u64 v[254:255], v[102:103], 0, v[98:99]
	v_readfirstlane_b32 s100, v121
	s_mov_b64 s[4:5], 0x80
	s_waitcnt vmcnt(0) lgkmcnt(0)
	s_barrier
	s_mov_b64 s[16:17], 0x5872080
	s_add_u32 m0, s100, 0x6000
	v_lshl_add_u64 v[106:107], v[252:253], 0, s[16:17]
	global_load_lds_dwordx4 v[106:107], off
	s_mov_b64 s[16:17], 0x589e080
	s_add_u32 m0, s100, 0x7000
	v_lshl_add_u64 v[106:107], v[252:253], 0, s[16:17]
	global_load_lds_dwordx4 v[106:107], off
	s_mov_b64 s[16:17], 0x58ca080
	s_add_u32 m0, s100, 0x8000
	v_lshl_add_u64 v[106:107], v[252:253], 0, s[16:17]
	global_load_lds_dwordx4 v[106:107], off
	s_mov_b64 s[16:17], 0x58f6080
	s_add_u32 m0, s100, 0x9000
	v_lshl_add_u64 v[106:107], v[252:253], 0, s[16:17]
	global_load_lds_dwordx4 v[106:107], off
	s_mov_b64 s[16:17], 0x5922080
	s_add_u32 m0, s100, 0xa000
	v_lshl_add_u64 v[106:107], v[252:253], 0, s[16:17]
	global_load_lds_dwordx4 v[106:107], off
	s_mov_b64 s[16:17], 0x594e080
	s_add_u32 m0, s100, 0xb000
	v_lshl_add_u64 v[106:107], v[252:253], 0, s[16:17]
	global_load_lds_dwordx4 v[106:107], off
	v_lshl_add_u64 v[252:253], v[252:253], 0, s[4:5]
	s_mov_b64 s[16:17], 0x1600080
	s_add_u32 m0, s100, 0x10000
	v_lshl_add_u64 v[106:107], v[254:255], 0, s[16:17]
	global_load_lds_dwordx4 v[106:107], off
	s_mov_b64 s[16:17], 0x162c080
	s_add_u32 m0, s100, 0x11000
	v_lshl_add_u64 v[106:107], v[254:255], 0, s[16:17]
	global_load_lds_dwordx4 v[106:107], off
	s_mov_b64 s[16:17], 0x1658080
	s_add_u32 m0, s100, 0x12000
	v_lshl_add_u64 v[106:107], v[254:255], 0, s[16:17]
	global_load_lds_dwordx4 v[106:107], off
	s_mov_b64 s[16:17], 0x1684080
	s_add_u32 m0, s100, 0x13000
	v_lshl_add_u64 v[106:107], v[254:255], 0, s[16:17]
	global_load_lds_dwordx4 v[106:107], off
	v_lshl_add_u64 v[254:255], v[254:255], 0, s[4:5]
	ds_read_b128 v[236:239], v166 offset:49152
	ds_read_b128 v[240:243], v166 offset:53248
	ds_read_b128 v[224:227], v162
	ds_read_b128 v[228:231], v162 offset:4096
	s_mov_b32 s15, 0
.Lgd_loop:
	ds_read_b128 v[232:235], v162 offset:8192
	s_waitcnt lgkmcnt(2)
	v_mfma_f32_32x32x16_bf16 v[80:95], v[224:227], v[236:239], v[80:95]
	v_mfma_f32_32x32x16_bf16 v[64:79], v[224:227], v[240:243], v[64:79]
	ds_read_b128 v[244:247], v167 offset:49152
	ds_read_b128 v[248:251], v167 offset:53248
	ds_read_b128 v[224:227], v163
	s_waitcnt lgkmcnt(4)
	v_mfma_f32_32x32x16_bf16 v[48:63], v[228:231], v[236:239], v[48:63]
	v_mfma_f32_32x32x16_bf16 v[32:47], v[228:231], v[240:243], v[32:47]
	ds_read_b128 v[228:231], v163 offset:4096
	s_waitcnt lgkmcnt(4)
	v_mfma_f32_32x32x16_bf16 v[16:31], v[232:235], v[236:239], v[16:31]
	v_mfma_f32_32x32x16_bf16 v[0:15], v[232:235], v[240:243], v[0:15]
	ds_read_b128 v[232:235], v163 offset:8192
	s_waitcnt lgkmcnt(2)
	v_mfma_f32_32x32x16_bf16 v[80:95], v[224:227], v[244:247], v[80:95]
	v_mfma_f32_32x32x16_bf16 v[64:79], v[224:227], v[248:251], v[64:79]
	ds_read_b128 v[236:239], v168 offset:49152
	ds_read_b128 v[240:243], v168 offset:53248
	ds_read_b128 v[224:227], v164
	s_waitcnt lgkmcnt(4)
	v_mfma_f32_32x32x16_bf16 v[48:63], v[228:231], v[244:247], v[48:63]
	v_mfma_f32_32x32x16_bf16 v[32:47], v[228:231], v[248:251], v[32:47]
	ds_read_b128 v[228:231], v164 offset:4096
	s_waitcnt lgkmcnt(4)
	v_mfma_f32_32x32x16_bf16 v[16:31], v[232:235], v[244:247], v[16:31]
	v_mfma_f32_32x32x16_bf16 v[0:15], v[232:235], v[248:251], v[0:15]
	ds_read_b128 v[232:235], v164 offset:8192
	s_waitcnt lgkmcnt(2)
	v_mfma_f32_32x32x16_bf16 v[80:95], v[224:227], v[236:239], v[80:95]
	v_mfma_f32_32x32x16_bf16 v[64:79], v[224:227], v[240:243], v[64:79]
	ds_read_b128 v[244:247], v169 offset:49152
	ds_read_b128 v[248:251], v169 offset:53248
	ds_read_b128 v[224:227], v165
	s_waitcnt lgkmcnt(4)
	v_mfma_f32_32x32x16_bf16 v[48:63], v[228:231], v[236:239], v[48:63]
	v_mfma_f32_32x32x16_bf16 v[32:47], v[228:231], v[240:243], v[32:47]
	ds_read_b128 v[228:231], v165 offset:4096
	s_waitcnt lgkmcnt(4)
	v_mfma_f32_32x32x16_bf16 v[16:31], v[232:235], v[236:239], v[16:31]
	v_mfma_f32_32x32x16_bf16 v[0:15], v[232:235], v[240:243], v[0:15]
	ds_read_b128 v[232:235], v165 offset:8192
	s_waitcnt lgkmcnt(2)
	v_mfma_f32_32x32x16_bf16 v[80:95], v[224:227], v[244:247], v[80:95]
	v_mfma_f32_32x32x16_bf16 v[64:79], v[224:227], v[248:251], v[64:79]
	s_waitcnt lgkmcnt(0)
	s_waitcnt vmcnt(0)
	s_barrier
; template <int EPI, int MI>
; DI void gemm_tile(const GemmDesc& g, int tm, int tn, char* smem) {
;     ...
;   const int rowA = wm * (32 * MI) + r, rowB = wn * 64 + r;
;   const int hk = hh ^ ((r & 7) ^ ((r >> 3) & 3));
;     ...
;   G_GLDS(0, 0);
;   asm volatile("s_waitcnt vmcnt(0)" ::: "memory");
;   __syncthreads();
;   for (int kt = 0; kt < nk; kt += 2) {
;     if (kt + 1 < nk) G_GLDS(kt + 1, 1);
;     G_COMPUTE(0);
;     asm volatile("s_waitcnt vmcnt(0)" ::: "memory");
;     __syncthreads();
;     if (kt + 1 < nk) {
;       if (kt + 2 < nk) G_GLDS(kt + 2, 0);
;       G_COMPUTE(1);
;       asm volatile("s_waitcnt vmcnt(0)" ::: "memory");
;       __syncthreads();
;     }
	s_cmp_eq_u32 s15, 42
	s_cbranch_scc1 .Lgd_noearly
	s_mov_b64 s[16:17], 0x5872080
	s_mov_b32 m0, s100
	v_lshl_add_u64 v[106:107], v[252:253], 0, s[16:17]
	global_load_lds_dwordx4 v[106:107], off
	s_mov_b64 s[16:17], 0x589e080
	s_add_u32 m0, s100, 0x1000
	v_lshl_add_u64 v[106:107], v[252:253], 0, s[16:17]
	global_load_lds_dwordx4 v[106:107], off
	s_mov_b64 s[16:17], 0x58ca080
	s_add_u32 m0, s100, 0x2000
	v_lshl_add_u64 v[106:107], v[252:253], 0, s[16:17]
	global_load_lds_dwordx4 v[106:107], off
	s_mov_b64 s[16:17], 0x58f6080
	s_add_u32 m0, s100, 0x3000
	v_lshl_add_u64 v[106:107], v[252:253], 0, s[16:17]
	global_load_lds_dwordx4 v[106:107], off
	s_mov_b64 s[16:17], 0x5922080
	s_add_u32 m0, s100, 0x4000
	v_lshl_add_u64 v[106:107], v[252:253], 0, s[16:17]
	global_load_lds_dwordx4 v[106:107], off
	s_mov_b64 s[16:17], 0x594e080
	s_add_u32 m0, s100, 0x5000
	v_lshl_add_u64 v[106:107], v[252:253], 0, s[16:17]
	global_load_lds_dwordx4 v[106:107], off
	v_lshl_add_u64 v[252:253], v[252:253], 0, s[4:5]
	s_mov_b64 s[16:17], 0x1600080
	s_add_u32 m0, s100, 0xc000
	v_lshl_add_u64 v[106:107], v[254:255], 0, s[16:17]
	global_load_lds_dwordx4 v[106:107], off
	s_mov_b64 s[16:17], 0x162c080
	s_add_u32 m0, s100, 0xd000
	v_lshl_add_u64 v[106:107], v[254:255], 0, s[16:17]
	global_load_lds_dwordx4 v[106:107], off
	s_mov_b64 s[16:17], 0x1658080
	s_add_u32 m0, s100, 0xe000
	v_lshl_add_u64 v[106:107], v[254:255], 0, s[16:17]
	global_load_lds_dwordx4 v[106:107], off
	s_mov_b64 s[16:17], 0x1684080
	s_add_u32 m0, s100, 0xf000
	v_lshl_add_u64 v[106:107], v[254:255], 0, s[16:17]
	global_load_lds_dwordx4 v[106:107], off
	v_lshl_add_u64 v[254:255], v[254:255], 0, s[4:5]
.Lgd_noearly:
	ds_read_b128 v[236:239], v170
	ds_read_b128 v[240:243], v170 offset:4096
	ds_read_b128 v[224:227], v162 offset:24576
	v_mfma_f32_32x32x16_bf16 v[48:63], v[228:231], v[244:247], v[48:63]
	v_mfma_f32_32x32x16_bf16 v[32:47], v[228:231], v[248:251], v[32:47]
	ds_read_b128 v[228:231], v162 offset:28672
	v_mfma_f32_32x32x16_bf16 v[16:31], v[232:235], v[244:247], v[16:31]
	v_mfma_f32_32x32x16_bf16 v[0:15], v[232:235], v[248:251], v[0:15]
	s_cmp_eq_u32 s15, 42
	s_cbranch_scc1 .Lgd_last
	ds_read_b128 v[232:235], v162 offset:32768
	s_waitcnt lgkmcnt(2)
	v_mfma_f32_32x32x16_bf16 v[80:95], v[224:227], v[236:239], v[80:95]
	v_mfma_f32_32x32x16_bf16 v[64:79], v[224:227], v[240:243], v[64:79]
	ds_read_b128 v[244:247], v171
	ds_read_b128 v[248:251], v171 offset:4096
	ds_read_b128 v[224:227], v163 offset:24576
	s_waitcnt lgkmcnt(4)
	v_mfma_f32_32x32x16_bf16 v[48:63], v[228:231], v[236:239], v[48:63]
	v_mfma_f32_32x32x16_bf16 v[32:47], v[228:231], v[240:243], v[32:47]
	ds_read_b128 v[228:231], v163 offset:28672
	s_waitcnt lgkmcnt(4)
	v_mfma_f32_32x32x16_bf16 v[16:31], v[232:235], v[236:239], v[16:31]
	v_mfma_f32_32x32x16_bf16 v[0:15], v[232:235], v[240:243], v[0:15]
	ds_read_b128 v[232:235], v163 offset:32768
	s_waitcnt lgkmcnt(2)
	v_mfma_f32_32x32x16_bf16 v[80:95], v[224:227], v[244:247], v[80:95]
	v_mfma_f32_32x32x16_bf16 v[64:79], v[224:227], v[248:251], v[64:79]
	ds_read_b128 v[236:239], v172
	ds_read_b128 v[240:243], v172 offset:4096
	ds_read_b128 v[224:227], v164 offset:24576
	s_waitcnt lgkmcnt(4)
	v_mfma_f32_32x32x16_bf16 v[48:63], v[228:231], v[244:247], v[48:63]
	v_mfma_f32_32x32x16_bf16 v[32:47], v[228:231], v[248:251], v[32:47]
	ds_read_b128 v[228:231], v164 offset:28672
	s_waitcnt lgkmcnt(4)
	v_mfma_f32_32x32x16_bf16 v[16:31], v[232:235], v[244:247], v[16:31]
	v_mfma_f32_32x32x16_bf16 v[0:15], v[232:235], v[248:251], v[0:15]
	ds_read_b128 v[232:235], v164 offset:32768
	s_waitcnt lgkmcnt(2)
	v_mfma_f32_32x32x16_bf16 v[80:95], v[224:227], v[236:239], v[80:95]
	v_mfma_f32_32x32x16_bf16 v[64:79], v[224:227], v[240:243], v[64:79]
	ds_read_b128 v[244:247], v173
	ds_read_b128 v[248:251], v173 offset:4096
	ds_read_b128 v[224:227], v165 offset:24576
	s_waitcnt lgkmcnt(4)
	v_mfma_f32_32x32x16_bf16 v[48:63], v[228:231], v[236:239], v[48:63]
	v_mfma_f32_32x32x16_bf16 v[32:47], v[228:231], v[240:243], v[32:47]
	ds_read_b128 v[228:231], v165 offset:28672
	s_waitcnt lgkmcnt(4)
	v_mfma_f32_32x32x16_bf16 v[16:31], v[232:235], v[236:239], v[16:31]
	v_mfma_f32_32x32x16_bf16 v[0:15], v[232:235], v[240:243], v[0:15]
	ds_read_b128 v[232:235], v165 offset:32768
	s_waitcnt lgkmcnt(2)
	v_mfma_f32_32x32x16_bf16 v[80:95], v[224:227], v[244:247], v[80:95]
	v_mfma_f32_32x32x16_bf16 v[64:79], v[224:227], v[248:251], v[64:79]
	s_waitcnt lgkmcnt(0)
	s_waitcnt vmcnt(0)
	s_barrier
	s_mov_b64 s[16:17], 0x5872080
	s_add_u32 m0, s100, 0x6000
	v_lshl_add_u64 v[106:107], v[252:253], 0, s[16:17]
	global_load_lds_dwordx4 v[106:107], off
	s_mov_b64 s[16:17], 0x589e080
	s_add_u32 m0, s100, 0x7000
	v_lshl_add_u64 v[106:107], v[252:253], 0, s[16:17]
	global_load_lds_dwordx4 v[106:107], off
	s_mov_b64 s[16:17], 0x58ca080
	s_add_u32 m0, s100, 0x8000
	v_lshl_add_u64 v[106:107], v[252:253], 0, s[16:17]
	global_load_lds_dwordx4 v[106:107], off
	s_mov_b64 s[16:17], 0x58f6080
	s_add_u32 m0, s100, 0x9000
	v_lshl_add_u64 v[106:107], v[252:253], 0, s[16:17]
	global_load_lds_dwordx4 v[106:107], off
	s_mov_b64 s[16:17], 0x5922080
	s_add_u32 m0, s100, 0xa000
	v_lshl_add_u64 v[106:107], v[252:253], 0, s[16:17]
	global_load_lds_dwordx4 v[106:107], off
	s_mov_b64 s[16:17], 0x594e080
	s_add_u32 m0, s100, 0xb000
	v_lshl_add_u64 v[106:107], v[252:253], 0, s[16:17]
	global_load_lds_dwordx4 v[106:107], off
	v_lshl_add_u64 v[252:253], v[252:253], 0, s[4:5]
	s_mov_b64 s[16:17], 0x1600080
	s_add_u32 m0, s100, 0x10000
	v_lshl_add_u64 v[106:107], v[254:255], 0, s[16:17]
	global_load_lds_dwordx4 v[106:107], off
	s_mov_b64 s[16:17], 0x162c080
	s_add_u32 m0, s100, 0x11000
	v_lshl_add_u64 v[106:107], v[254:255], 0, s[16:17]
	global_load_lds_dwordx4 v[106:107], off
	s_mov_b64 s[16:17], 0x1658080
	s_add_u32 m0, s100, 0x12000
	v_lshl_add_u64 v[106:107], v[254:255], 0, s[16:17]
	global_load_lds_dwordx4 v[106:107], off
	s_mov_b64 s[16:17], 0x1684080
	s_add_u32 m0, s100, 0x13000
	v_lshl_add_u64 v[106:107], v[254:255], 0, s[16:17]
	global_load_lds_dwordx4 v[106:107], off
	v_lshl_add_u64 v[254:255], v[254:255], 0, s[4:5]
	ds_read_b128 v[236:239], v166 offset:49152
	ds_read_b128 v[240:243], v166 offset:53248
	ds_read_b128 v[224:227], v162
	v_mfma_f32_32x32x16_bf16 v[48:63], v[228:231], v[244:247], v[48:63]
	v_mfma_f32_32x32x16_bf16 v[32:47], v[228:231], v[248:251], v[32:47]
	ds_read_b128 v[228:231], v162 offset:4096
	v_mfma_f32_32x32x16_bf16 v[16:31], v[232:235], v[244:247], v[16:31]
	v_mfma_f32_32x32x16_bf16 v[0:15], v[232:235], v[248:251], v[0:15]
	s_add_u32 s15, s15, 2
	s_branch .Lgd_loop

; template <int EPI, int MI>
; DI void gemm_tile(const GemmDesc& g, int tm, int tn, char* smem) {
;     ...
;   const int tid = get_tid(), lane = tid & 63, wave = tid >> 6, r = lane & 31, hh = lane >> 5;
;   const int wm = wave >> 1, wn = wave & 1;
;   const int m0 = tm * BM, n0 = tn * 128;
;   const int nk = g.K >> 6;
;   f32x16 acc[MI][2];
; #pragma unroll
;   for (int a = 0; a < MI; ++a)
; #pragma unroll
;     for (int b = 0; b < 2; ++b)
; #pragma unroll
;       for (int i = 0; i < 16; ++i) acc[a][b][i] = 0.f;
;   const int srow = tid >> 3;
;   const int schunk = (tid & 7) ^ ((srow & 7) ^ ((srow >> 3) & 3));
;     ...
;   const int rowA = wm * (32 * MI) + r, rowB = wn * 64 + r;
;   const int hk = hh ^ ((r & 7) ^ ((r >> 3) & 3));
;     ...
;   G_GLDS(0, 0);
;   asm volatile("s_waitcnt vmcnt(0)" ::: "memory");
;   __syncthreads();
; template <int EPI, int MI>
; DI void gemm_phase(const GemmDesc& g, char* smem, int vb, int nvb) {
;     ...
;   for (int q = start; q < local; q += step) {
;     const int mg = q / per;
;     const int rem = q - mg * per;
;     const int tn = rem / PM;
;     const int tm = mbase + mg * PM + (rem - tn * PM);
.LBB0_1421:
	s_abs_i32 s1, s5
	v_readlane_b32 s15, v219, 45
	s_mul_hi_u32 s15, s1, s15
	v_readlane_b32 s18, v219, 44
	s_mul_i32 s16, s15, s18
	s_sub_i32 s1, s1, s16
	s_ashr_i32 s0, s5, 31
	s_add_i32 s16, s15, 1
	s_sub_i32 s17, s1, s18
	s_cmp_ge_u32 s1, s18
	s_cselect_b32 s15, s16, s15
	s_cselect_b32 s1, s17, s1
	s_add_i32 s16, s15, 1
	s_cmp_ge_u32 s1, s18
	s_cselect_b32 s1, s16, s15
	s_xor_b32 s1, s1, s0
	s_sub_i32 s15, s1, s0
	s_mul_i32 s16, s15, s18
	s_sub_i32 s16, s5, s16
	s_abs_i32 s18, s16
	v_readlane_b32 s19, v219, 46
	s_mul_hi_u32 s19, s18, s19
	v_readlane_b32 s40, v218, 32
	s_mul_i32 s38, s19, s40
	s_sub_i32 s18, s18, s38
	s_ashr_i32 s17, s16, 31
	s_add_i32 s38, s19, 1
	s_sub_i32 s39, s18, s40
	s_cmp_ge_u32 s18, s40
	s_cselect_b32 s19, s38, s19
	s_cselect_b32 s18, s39, s18
	s_add_i32 s38, s19, 1
	s_cmp_ge_u32 s18, s40
	s_cselect_b32 s18, s38, s19
	s_xor_b32 s18, s18, s17
	s_sub_i32 s39, s18, s17
	s_sub_i32 s15, s15, s39
	v_mov_b32_e32 v6, v132
	s_mul_i32 s15, s15, s40
	s_add_i32 s16, s16, s54
	s_add_i32 s38, s16, s15
	v_ashrrev_i32_e32 v97, 3, v6
	v_ashrrev_i32_e32 v120, 7, v6
	v_bfe_u32 v0, v6, 6, 2
	v_xor_b32_e32 v1, v97, v6
	s_mulk_i32 s38, 0xc0
	v_and_b32_e32 v121, 31, v6
	v_bitop3_b32 v2, v1, v0, 7 bitop3:0x6c
	v_mul_lo_u32 v0, v120, s6
	v_and_b32_e32 v115, 7, v6
	v_or_b32_e32 v8, v0, v121
	v_lshrrev_b32_e32 v0, 3, v6
	s_waitcnt vmcnt(10)
	v_add_u32_e32 v98, s38, v97
	v_bfe_u32 v122, v6, 5, 1
	v_bitop3_b32 v0, v0, v115, 3 bitop3:0x6c
	v_ashrrev_i32_e32 v99, 31, v98
	v_readlane_b32 s40, v223, 59
	v_xor_b32_e32 v9, v0, v122
	v_lshlrev_b64 v[0:1], 11, v[98:99]
	v_readlane_b32 s41, v223, 60
	v_lshlrev_b32_e32 v100, 4, v2
	v_lshl_add_u32 v2, s39, 7, v97
	v_lshlrev_b32_e32 v99, 4, v6
	v_lshl_add_u64 v[0:1], s[40:41], 0, v[0:1]
	v_ashrrev_i32_e32 v3, 31, v2
	v_readlane_b32 s40, v220, 54
	v_add_u32_e32 v124, 0, v99
	v_mov_b32_e32 v101, v96
	v_lshlrev_b64 v[2:3], 11, v[2:3]
	v_readlane_b32 s41, v220, 55
	v_readfirstlane_b32 s15, v124
	v_add_u32_e32 v125, 0x1000, v124
	v_lshl_add_u64 v[0:1], v[0:1], 0, v[100:101]
	v_lshl_add_u64 v[4:5], s[40:41], 0, v[2:3]
	s_mov_b32 m0, s15
	s_mov_b64 s[40:41], 0x10000
	v_readfirstlane_b32 s15, v125
	v_add_u32_e32 v126, 0x2000, v124
	v_bfe_u32 v123, v6, 6, 1
	global_load_lds_dwordx4 v[0:1], off
	v_lshl_add_u64 v[6:7], v[0:1], 0, s[40:41]
	s_mov_b32 m0, s15
	s_mov_b64 s[42:43], 0x20000
	v_readfirstlane_b32 s15, v126
	v_add_u32_e32 v127, 0x3000, v124
	global_load_lds_dwordx4 v[6:7], off
	v_lshl_add_u64 v[6:7], v[0:1], 0, s[42:43]
	s_mov_b32 m0, s15
	s_mov_b64 s[44:45], 0x30000
	v_readfirstlane_b32 s15, v127
	v_add_u32_e32 v128, 0x4000, v124
	global_load_lds_dwordx4 v[6:7], off
	v_lshl_add_u64 v[6:7], v[0:1], 0, s[44:45]
	s_mov_b32 m0, s15
	s_mov_b64 s[46:47], 0x40000
	v_readfirstlane_b32 s15, v128
	v_add_u32_e32 v129, 0x5000, v124
	global_load_lds_dwordx4 v[6:7], off
	v_lshl_add_u64 v[6:7], v[0:1], 0, s[46:47]
	s_mov_b32 m0, s15
	s_mov_b64 s[46:47], 0x50000
	v_readfirstlane_b32 s15, v129
	v_add_u32_e32 v130, 0xc000, v124
	global_load_lds_dwordx4 v[6:7], off
	v_lshl_add_u64 v[0:1], v[0:1], 0, s[46:47]
	s_mov_b32 m0, s15
	v_readfirstlane_b32 s15, v130
	v_add_u32_e32 v131, 0xd000, v124
	global_load_lds_dwordx4 v[0:1], off
	v_lshl_add_u64 v[0:1], v[4:5], 0, v[100:101]
	s_mov_b32 m0, s15
	v_readfirstlane_b32 s15, v131
	v_add_u32_e32 v153, 0xe000, v124
	global_load_lds_dwordx4 v[0:1], off
	v_lshl_add_u64 v[4:5], v[0:1], 0, s[40:41]
	s_mov_b32 m0, s15
	v_readfirstlane_b32 s15, v153
	v_add_u32_e32 v154, 0xf000, v124
	global_load_lds_dwordx4 v[4:5], off
	v_lshl_add_u64 v[4:5], v[0:1], 0, s[42:43]
	s_mov_b32 m0, s15
	v_readfirstlane_b32 s15, v154
	global_load_lds_dwordx4 v[4:5], off
	v_lshl_add_u64 v[0:1], v[0:1], 0, s[44:45]
	s_mov_b32 m0, s15
	s_mul_i32 s0, s0, 43
	global_load_lds_dwordx4 v[0:1], off
	s_add_i32 s17, s17, s0
	s_sub_i32 s0, s17, s18
	s_mul_i32 s1, s1, 43
	s_sub_i32 s0, s0, s1
	v_readlane_b32 s1, v218, 33
	v_lshlrev_b32_e32 v0, 7, v121
	s_mul_i32 s0, s1, s0
	v_lshl_or_b32 v0, v123, 13, v0
	s_add_i32 s0, s0, s4
	v_add_u32_e32 v156, 0, v0
	v_add_u32_e32 v158, s10, v0
	v_add_u32_e32 v0, s0, v97
	v_ashrrev_i32_e32 v1, 31, v0
	s_waitcnt vmcnt(0)
	v_lshlrev_b64 v[0:1], 11, v[0:1]
	v_lshlrev_b32_e32 v157, 4, v9
	s_waitcnt vmcnt(0)
; template <int EPI, int MI>
; DI void gemm_tile(const GemmDesc& g, int tm, int tn, char* smem) {
;     ...
;   f32x16 acc[MI][2];
; #pragma unroll
;   for (int a = 0; a < MI; ++a)
; #pragma unroll
;     for (int b = 0; b < 2; ++b)
; #pragma unroll
;       for (int i = 0; i < 16; ++i) acc[a][b][i] = 0.f;
;   const int srow = tid >> 3;
;   const int schunk = (tid & 7) ^ ((srow & 7) ^ ((srow >> 3) & 3));
;     ...
;   const int rowA = wm * (32 * MI) + r, rowB = wn * 64 + r;
;   const int hk = hh ^ ((r & 7) ^ ((r >> 3) & 3));
;     ...
;   G_GLDS(0, 0);
;   asm volatile("s_waitcnt vmcnt(0)" ::: "memory");
;   __syncthreads();
;   for (int kt = 0; kt < nk; kt += 2) {
;     if (kt + 1 < nk) G_GLDS(kt + 1, 1);
	v_lshl_add_u64 v[102:103], s[70:71], 0, v[0:1]
	v_mov_b32_e32 v0, 0
	v_lshl_add_u32 v155, v8, 7, 0
	v_xor_b32_e32 v159, 32, v157
	v_xor_b32_e32 v160, 64, v157
	v_xor_b32_e32 v161, 0x60, v157
	v_lshl_add_u64 v[104:105], s[70:71], 0, v[2:3]
	s_mov_b32 s15, 0
	v_mov_b32_e32 v1, v0
	v_mov_b32_e32 v2, v0
	v_mov_b32_e32 v3, v0
	v_mov_b32_e32 v4, v0
	v_mov_b32_e32 v5, v0
	v_mov_b32_e32 v6, v0
	v_mov_b32_e32 v7, v0
	v_mov_b32_e32 v8, v0
	v_mov_b32_e32 v9, v0
	v_mov_b32_e32 v10, v0
	v_mov_b32_e32 v11, v0
	v_mov_b32_e32 v12, v0
	v_mov_b32_e32 v13, v0
	v_mov_b32_e32 v14, v0
	v_mov_b32_e32 v15, v0
	v_mov_b32_e32 v16, v0
	v_mov_b32_e32 v17, v0
	v_mov_b32_e32 v18, v0
	v_mov_b32_e32 v19, v0
	v_mov_b32_e32 v20, v0
	v_mov_b32_e32 v21, v0
	v_mov_b32_e32 v22, v0
	v_mov_b32_e32 v23, v0
	v_mov_b32_e32 v24, v0
	v_mov_b32_e32 v25, v0
	v_mov_b32_e32 v26, v0
	v_mov_b32_e32 v27, v0
	v_mov_b32_e32 v28, v0
	v_mov_b32_e32 v29, v0
	v_mov_b32_e32 v30, v0
	v_mov_b32_e32 v31, v0
	v_mov_b32_e32 v32, v0
	v_mov_b32_e32 v33, v0
	v_mov_b32_e32 v34, v0
	v_mov_b32_e32 v35, v0
	v_mov_b32_e32 v36, v0
	v_mov_b32_e32 v37, v0
	v_mov_b32_e32 v38, v0
	v_mov_b32_e32 v39, v0
	v_mov_b32_e32 v40, v0
	v_mov_b32_e32 v41, v0
	v_mov_b32_e32 v42, v0
	v_mov_b32_e32 v43, v0
	v_mov_b32_e32 v44, v0
	v_mov_b32_e32 v45, v0
	v_mov_b32_e32 v46, v0
	v_mov_b32_e32 v47, v0
	v_mov_b32_e32 v48, v0
	v_mov_b32_e32 v49, v0
	v_mov_b32_e32 v50, v0
	v_mov_b32_e32 v51, v0
	v_mov_b32_e32 v52, v0
	v_mov_b32_e32 v53, v0
	v_mov_b32_e32 v54, v0
	v_mov_b32_e32 v55, v0
	v_mov_b32_e32 v56, v0
	v_mov_b32_e32 v57, v0
	v_mov_b32_e32 v58, v0
	v_mov_b32_e32 v59, v0
	v_mov_b32_e32 v60, v0
	v_mov_b32_e32 v61, v0
	v_mov_b32_e32 v62, v0
	v_mov_b32_e32 v63, v0
	v_mov_b32_e32 v64, v0
	v_mov_b32_e32 v65, v0
	v_mov_b32_e32 v66, v0
	v_mov_b32_e32 v67, v0
	v_mov_b32_e32 v68, v0
	v_mov_b32_e32 v69, v0
	v_mov_b32_e32 v70, v0
	v_mov_b32_e32 v71, v0
	v_mov_b32_e32 v72, v0
	v_mov_b32_e32 v73, v0
	v_mov_b32_e32 v74, v0
	v_mov_b32_e32 v75, v0
	v_mov_b32_e32 v76, v0
	v_mov_b32_e32 v77, v0
	v_mov_b32_e32 v78, v0
	v_mov_b32_e32 v79, v0
	v_mov_b32_e32 v80, v0
	v_mov_b32_e32 v81, v0
	v_mov_b32_e32 v82, v0
	v_mov_b32_e32 v83, v0
	v_mov_b32_e32 v84, v0
	v_mov_b32_e32 v85, v0
	v_mov_b32_e32 v86, v0
	v_mov_b32_e32 v87, v0
	v_mov_b32_e32 v88, v0
	v_mov_b32_e32 v89, v0
	v_mov_b32_e32 v90, v0
	v_mov_b32_e32 v91, v0
	v_mov_b32_e32 v92, v0
	v_mov_b32_e32 v93, v0
	v_mov_b32_e32 v94, v0
	v_mov_b32_e32 v95, v0
	v_add_u32_e32 v162, v155, v157
	v_add_u32_e32 v163, v155, v159
	v_add_u32_e32 v164, v155, v160
	v_add_u32_e32 v165, v155, v161
	v_add_u32_e32 v166, v156, v157
	v_add_u32_e32 v167, v156, v159
	v_add_u32_e32 v168, v156, v160
	v_add_u32_e32 v169, v156, v161
	v_add_u32_e32 v170, v158, v157
	v_add_u32_e32 v171, v158, v159
	v_add_u32_e32 v172, v158, v160
	v_add_u32_e32 v173, v158, v161
	v_lshl_add_u64 v[252:253], v[102:103], 0, v[100:101]
	v_lshl_add_u64 v[254:255], v[104:105], 0, v[100:101]
	v_readfirstlane_b32 s100, v124
	s_mov_b64 s[0:1], 0x80
	s_waitcnt vmcnt(0) lgkmcnt(0)
	s_barrier
	s_add_u32 m0, s100, 0x6000
	v_lshl_add_u64 v[106:107], v[252:253], 0, s[96:97]
	global_load_lds_dwordx4 v[106:107], off
	s_add_u32 m0, s100, 0x7000
	v_lshl_add_u64 v[106:107], v[252:253], 0, s[50:51]
	global_load_lds_dwordx4 v[106:107], off
	s_add_u32 m0, s100, 0x8000
	v_lshl_add_u64 v[106:107], v[252:253], 0, s[24:25]
	global_load_lds_dwordx4 v[106:107], off
	s_add_u32 m0, s100, 0x9000
	v_lshl_add_u64 v[106:107], v[252:253], 0, s[26:27]
	global_load_lds_dwordx4 v[106:107], off
	s_add_u32 m0, s100, 0xa000
	v_lshl_add_u64 v[106:107], v[252:253], 0, s[28:29]
	global_load_lds_dwordx4 v[106:107], off
	s_add_u32 m0, s100, 0xb000
	v_lshl_add_u64 v[106:107], v[252:253], 0, s[30:31]
	global_load_lds_dwordx4 v[106:107], off
	v_lshl_add_u64 v[252:253], v[252:253], 0, s[0:1]
	s_mov_b64 s[16:17], 0xb00080
	s_add_u32 m0, s100, 0x10000
	v_lshl_add_u64 v[106:107], v[254:255], 0, s[16:17]
	global_load_lds_dwordx4 v[106:107], off
	s_mov_b64 s[16:17], 0xb10080
	s_add_u32 m0, s100, 0x11000
	v_lshl_add_u64 v[106:107], v[254:255], 0, s[16:17]
	global_load_lds_dwordx4 v[106:107], off
	s_mov_b64 s[16:17], 0xb20080
	s_add_u32 m0, s100, 0x12000
	v_lshl_add_u64 v[106:107], v[254:255], 0, s[16:17]
	global_load_lds_dwordx4 v[106:107], off
	s_mov_b64 s[16:17], 0xb30080
	s_add_u32 m0, s100, 0x13000
	v_lshl_add_u64 v[106:107], v[254:255], 0, s[16:17]
	global_load_lds_dwordx4 v[106:107], off
	v_lshl_add_u64 v[254:255], v[254:255], 0, s[0:1]
	ds_read_b128 v[236:239], v166 offset:49152
	ds_read_b128 v[240:243], v166 offset:53248
	ds_read_b128 v[224:227], v162
	ds_read_b128 v[228:231], v162 offset:4096
	s_mov_b32 s101, 0
; template <int EPI, int MI>
; DI void gemm_tile(const GemmDesc& g, int tm, int tn, char* smem) {
;     ...
;   const int rowA = wm * (32 * MI) + r, rowB = wn * 64 + r;
;   const int hk = hh ^ ((r & 7) ^ ((r >> 3) & 3));
;     ...
;   G_GLDS(0, 0);
;   asm volatile("s_waitcnt vmcnt(0)" ::: "memory");
;   __syncthreads();
;   for (int kt = 0; kt < nk; kt += 2) {
;     if (kt + 1 < nk) G_GLDS(kt + 1, 1);
;     G_COMPUTE(0);
;     asm volatile("s_waitcnt vmcnt(0)" ::: "memory");
;     __syncthreads();
;     if (kt + 1 < nk) {
;       if (kt + 2 < nk) G_GLDS(kt + 2, 0);
.Lgb_loop:
	ds_read_b128 v[232:235], v162 offset:8192
	s_waitcnt lgkmcnt(2)
	v_mfma_f32_32x32x16_bf16 v[80:95], v[224:227], v[236:239], v[80:95]
	v_mfma_f32_32x32x16_bf16 v[64:79], v[224:227], v[240:243], v[64:79]
	ds_read_b128 v[244:247], v167 offset:49152
	ds_read_b128 v[248:251], v167 offset:53248
	ds_read_b128 v[224:227], v163
	s_waitcnt lgkmcnt(4)
	v_mfma_f32_32x32x16_bf16 v[48:63], v[228:231], v[236:239], v[48:63]
	v_mfma_f32_32x32x16_bf16 v[32:47], v[228:231], v[240:243], v[32:47]
	ds_read_b128 v[228:231], v163 offset:4096
	s_waitcnt lgkmcnt(4)
	v_mfma_f32_32x32x16_bf16 v[16:31], v[232:235], v[236:239], v[16:31]
	v_mfma_f32_32x32x16_bf16 v[0:15], v[232:235], v[240:243], v[0:15]
	ds_read_b128 v[232:235], v163 offset:8192
	s_waitcnt lgkmcnt(2)
	v_mfma_f32_32x32x16_bf16 v[80:95], v[224:227], v[244:247], v[80:95]
	v_mfma_f32_32x32x16_bf16 v[64:79], v[224:227], v[248:251], v[64:79]
	ds_read_b128 v[236:239], v168 offset:49152
	ds_read_b128 v[240:243], v168 offset:53248
	ds_read_b128 v[224:227], v164
	s_waitcnt lgkmcnt(4)
	v_mfma_f32_32x32x16_bf16 v[48:63], v[228:231], v[244:247], v[48:63]
	v_mfma_f32_32x32x16_bf16 v[32:47], v[228:231], v[248:251], v[32:47]
	ds_read_b128 v[228:231], v164 offset:4096
	s_waitcnt lgkmcnt(4)
	v_mfma_f32_32x32x16_bf16 v[16:31], v[232:235], v[244:247], v[16:31]
	v_mfma_f32_32x32x16_bf16 v[0:15], v[232:235], v[248:251], v[0:15]
	ds_read_b128 v[232:235], v164 offset:8192
	s_waitcnt lgkmcnt(2)
	v_mfma_f32_32x32x16_bf16 v[80:95], v[224:227], v[236:239], v[80:95]
	v_mfma_f32_32x32x16_bf16 v[64:79], v[224:227], v[240:243], v[64:79]
	ds_read_b128 v[244:247], v169 offset:49152
	ds_read_b128 v[248:251], v169 offset:53248
	ds_read_b128 v[224:227], v165
	s_waitcnt lgkmcnt(4)
	v_mfma_f32_32x32x16_bf16 v[48:63], v[228:231], v[236:239], v[48:63]
	v_mfma_f32_32x32x16_bf16 v[32:47], v[228:231], v[240:243], v[32:47]
	ds_read_b128 v[228:231], v165 offset:4096
	s_waitcnt lgkmcnt(4)
	v_mfma_f32_32x32x16_bf16 v[16:31], v[232:235], v[236:239], v[16:31]
	v_mfma_f32_32x32x16_bf16 v[0:15], v[232:235], v[240:243], v[0:15]
	ds_read_b128 v[232:235], v165 offset:8192
	s_waitcnt lgkmcnt(2)
	v_mfma_f32_32x32x16_bf16 v[80:95], v[224:227], v[244:247], v[80:95]
	v_mfma_f32_32x32x16_bf16 v[64:79], v[224:227], v[248:251], v[64:79]
	s_waitcnt lgkmcnt(0)
	s_waitcnt vmcnt(0)
	s_barrier
	s_cmp_eq_u32 s101, 14
	s_cbranch_scc1 .Lgb_noearly
	s_mov_b32 m0, s100
	v_lshl_add_u64 v[106:107], v[252:253], 0, s[96:97]
	global_load_lds_dwordx4 v[106:107], off
	s_add_u32 m0, s100, 0x1000
	v_lshl_add_u64 v[106:107], v[252:253], 0, s[50:51]
	global_load_lds_dwordx4 v[106:107], off
	s_add_u32 m0, s100, 0x2000
	v_lshl_add_u64 v[106:107], v[252:253], 0, s[24:25]
	global_load_lds_dwordx4 v[106:107], off
	s_add_u32 m0, s100, 0x3000
	v_lshl_add_u64 v[106:107], v[252:253], 0, s[26:27]
	global_load_lds_dwordx4 v[106:107], off
	s_add_u32 m0, s100, 0x4000
	v_lshl_add_u64 v[106:107], v[252:253], 0, s[28:29]
	global_load_lds_dwordx4 v[106:107], off
	s_add_u32 m0, s100, 0x5000
	v_lshl_add_u64 v[106:107], v[252:253], 0, s[30:31]
	global_load_lds_dwordx4 v[106:107], off
	v_lshl_add_u64 v[252:253], v[252:253], 0, s[0:1]
	s_mov_b64 s[16:17], 0xb00080
	s_add_u32 m0, s100, 0xc000
	v_lshl_add_u64 v[106:107], v[254:255], 0, s[16:17]
	global_load_lds_dwordx4 v[106:107], off
	s_mov_b64 s[16:17], 0xb10080
	s_add_u32 m0, s100, 0xd000
	v_lshl_add_u64 v[106:107], v[254:255], 0, s[16:17]
	global_load_lds_dwordx4 v[106:107], off
	s_mov_b64 s[16:17], 0xb20080
	s_add_u32 m0, s100, 0xe000
	v_lshl_add_u64 v[106:107], v[254:255], 0, s[16:17]
	global_load_lds_dwordx4 v[106:107], off
	s_mov_b64 s[16:17], 0xb30080
	s_add_u32 m0, s100, 0xf000
	v_lshl_add_u64 v[106:107], v[254:255], 0, s[16:17]
	global_load_lds_dwordx4 v[106:107], off
	v_lshl_add_u64 v[254:255], v[254:255], 0, s[0:1]
; template <int EPI, int MI>
; DI void gemm_tile(const GemmDesc& g, int tm, int tn, char* smem) {
;     ...
;   const int rowA = wm * (32 * MI) + r, rowB = wn * 64 + r;
;   const int hk = hh ^ ((r & 7) ^ ((r >> 3) & 3));
;     ...
;   G_GLDS(0, 0);
;   asm volatile("s_waitcnt vmcnt(0)" ::: "memory");
;   __syncthreads();
;   for (int kt = 0; kt < nk; kt += 2) {
;     if (kt + 1 < nk) G_GLDS(kt + 1, 1);
;     G_COMPUTE(0);
;     asm volatile("s_waitcnt vmcnt(0)" ::: "memory");
;     __syncthreads();
;     if (kt + 1 < nk) {
;       if (kt + 2 < nk) G_GLDS(kt + 2, 0);
;       G_COMPUTE(1);
;       asm volatile("s_waitcnt vmcnt(0)" ::: "memory");
;       __syncthreads();
;     }
.Lgb_noearly:
	ds_read_b128 v[236:239], v170
	ds_read_b128 v[240:243], v170 offset:4096
	ds_read_b128 v[224:227], v162 offset:24576
	v_mfma_f32_32x32x16_bf16 v[48:63], v[228:231], v[244:247], v[48:63]
	v_mfma_f32_32x32x16_bf16 v[32:47], v[228:231], v[248:251], v[32:47]
	ds_read_b128 v[228:231], v162 offset:28672
	v_mfma_f32_32x32x16_bf16 v[16:31], v[232:235], v[244:247], v[16:31]
	v_mfma_f32_32x32x16_bf16 v[0:15], v[232:235], v[248:251], v[0:15]
	s_cmp_eq_u32 s101, 14
	s_cbranch_scc1 .Lgb_last
	ds_read_b128 v[232:235], v162 offset:32768
	s_waitcnt lgkmcnt(2)
	v_mfma_f32_32x32x16_bf16 v[80:95], v[224:227], v[236:239], v[80:95]
	v_mfma_f32_32x32x16_bf16 v[64:79], v[224:227], v[240:243], v[64:79]
	ds_read_b128 v[244:247], v171
	ds_read_b128 v[248:251], v171 offset:4096
	ds_read_b128 v[224:227], v163 offset:24576
	s_waitcnt lgkmcnt(4)
	v_mfma_f32_32x32x16_bf16 v[48:63], v[228:231], v[236:239], v[48:63]
	v_mfma_f32_32x32x16_bf16 v[32:47], v[228:231], v[240:243], v[32:47]
	ds_read_b128 v[228:231], v163 offset:28672
	s_waitcnt lgkmcnt(4)
	v_mfma_f32_32x32x16_bf16 v[16:31], v[232:235], v[236:239], v[16:31]
	v_mfma_f32_32x32x16_bf16 v[0:15], v[232:235], v[240:243], v[0:15]
	ds_read_b128 v[232:235], v163 offset:32768
	s_waitcnt lgkmcnt(2)
	v_mfma_f32_32x32x16_bf16 v[80:95], v[224:227], v[244:247], v[80:95]
	v_mfma_f32_32x32x16_bf16 v[64:79], v[224:227], v[248:251], v[64:79]
	ds_read_b128 v[236:239], v172
	ds_read_b128 v[240:243], v172 offset:4096
	ds_read_b128 v[224:227], v164 offset:24576
	s_waitcnt lgkmcnt(4)
	v_mfma_f32_32x32x16_bf16 v[48:63], v[228:231], v[244:247], v[48:63]
	v_mfma_f32_32x32x16_bf16 v[32:47], v[228:231], v[248:251], v[32:47]
	ds_read_b128 v[228:231], v164 offset:28672
	s_waitcnt lgkmcnt(4)
	v_mfma_f32_32x32x16_bf16 v[16:31], v[232:235], v[244:247], v[16:31]
	v_mfma_f32_32x32x16_bf16 v[0:15], v[232:235], v[248:251], v[0:15]
	ds_read_b128 v[232:235], v164 offset:32768
	s_waitcnt lgkmcnt(2)
	v_mfma_f32_32x32x16_bf16 v[80:95], v[224:227], v[236:239], v[80:95]
	v_mfma_f32_32x32x16_bf16 v[64:79], v[224:227], v[240:243], v[64:79]
	ds_read_b128 v[244:247], v173
	ds_read_b128 v[248:251], v173 offset:4096
	ds_read_b128 v[224:227], v165 offset:24576
	s_waitcnt lgkmcnt(4)
	v_mfma_f32_32x32x16_bf16 v[48:63], v[228:231], v[236:239], v[48:63]
	v_mfma_f32_32x32x16_bf16 v[32:47], v[228:231], v[240:243], v[32:47]
	ds_read_b128 v[228:231], v165 offset:28672
	s_waitcnt lgkmcnt(4)
	v_mfma_f32_32x32x16_bf16 v[16:31], v[232:235], v[236:239], v[16:31]
	v_mfma_f32_32x32x16_bf16 v[0:15], v[232:235], v[240:243], v[0:15]
	ds_read_b128 v[232:235], v165 offset:32768
	s_waitcnt lgkmcnt(2)
	v_mfma_f32_32x32x16_bf16 v[80:95], v[224:227], v[244:247], v[80:95]
	v_mfma_f32_32x32x16_bf16 v[64:79], v[224:227], v[248:251], v[64:79]
	s_waitcnt lgkmcnt(0)
	s_waitcnt vmcnt(0)
	s_barrier
	s_add_u32 m0, s100, 0x6000
	v_lshl_add_u64 v[106:107], v[252:253], 0, s[96:97]
	global_load_lds_dwordx4 v[106:107], off
	s_add_u32 m0, s100, 0x7000
	v_lshl_add_u64 v[106:107], v[252:253], 0, s[50:51]
	global_load_lds_dwordx4 v[106:107], off
	s_add_u32 m0, s100, 0x8000
	v_lshl_add_u64 v[106:107], v[252:253], 0, s[24:25]
	global_load_lds_dwordx4 v[106:107], off
	s_add_u32 m0, s100, 0x9000
	v_lshl_add_u64 v[106:107], v[252:253], 0, s[26:27]
	global_load_lds_dwordx4 v[106:107], off
	s_add_u32 m0, s100, 0xa000
	v_lshl_add_u64 v[106:107], v[252:253], 0, s[28:29]
	global_load_lds_dwordx4 v[106:107], off
	s_add_u32 m0, s100, 0xb000
	v_lshl_add_u64 v[106:107], v[252:253], 0, s[30:31]
	global_load_lds_dwordx4 v[106:107], off
	v_lshl_add_u64 v[252:253], v[252:253], 0, s[0:1]
	s_mov_b64 s[16:17], 0xb00080
	s_add_u32 m0, s100, 0x10000
	v_lshl_add_u64 v[106:107], v[254:255], 0, s[16:17]
	global_load_lds_dwordx4 v[106:107], off
	s_mov_b64 s[16:17], 0xb10080
	s_add_u32 m0, s100, 0x11000
	v_lshl_add_u64 v[106:107], v[254:255], 0, s[16:17]
	global_load_lds_dwordx4 v[106:107], off
	s_mov_b64 s[16:17], 0xb20080
	s_add_u32 m0, s100, 0x12000
	v_lshl_add_u64 v[106:107], v[254:255], 0, s[16:17]
	global_load_lds_dwordx4 v[106:107], off
	s_mov_b64 s[16:17], 0xb30080
	s_add_u32 m0, s100, 0x13000
	v_lshl_add_u64 v[106:107], v[254:255], 0, s[16:17]
	global_load_lds_dwordx4 v[106:107], off
	v_lshl_add_u64 v[254:255], v[254:255], 0, s[0:1]
	ds_read_b128 v[236:239], v166 offset:49152
	ds_read_b128 v[240:243], v166 offset:53248
	ds_read_b128 v[224:227], v162
	v_mfma_f32_32x32x16_bf16 v[48:63], v[228:231], v[244:247], v[48:63]
	v_mfma_f32_32x32x16_bf16 v[32:47], v[228:231], v[248:251], v[32:47]
	ds_read_b128 v[228:231], v162 offset:4096
	v_mfma_f32_32x32x16_bf16 v[16:31], v[232:235], v[244:247], v[16:31]
	v_mfma_f32_32x32x16_bf16 v[0:15], v[232:235], v[248:251], v[0:15]
	s_add_u32 s101, s101, 2
	s_branch .Lgb_loop

; template <int EPI, int MI>
; DI void gemm_tile(const GemmDesc& g, int tm, int tn, char* smem) {
;     ...
;   const int tid = get_tid(), lane = tid & 63, wave = tid >> 6, r = lane & 31, hh = lane >> 5;
;   const int wm = wave >> 1, wn = wave & 1;
;   const int m0 = tm * BM, n0 = tn * 128;
;   const int nk = g.K >> 6;
;   f32x16 acc[MI][2];
; #pragma unroll
;   for (int a = 0; a < MI; ++a)
; #pragma unroll
;     for (int b = 0; b < 2; ++b)
; #pragma unroll
;       for (int i = 0; i < 16; ++i) acc[a][b][i] = 0.f;
;   const int srow = tid >> 3;
;   const int schunk = (tid & 7) ^ ((srow & 7) ^ ((srow >> 3) & 3));
;     ...
;   const int rowA = wm * (32 * MI) + r, rowB = wn * 64 + r;
;   const int hk = hh ^ ((r & 7) ^ ((r >> 3) & 3));
;     ...
;   G_GLDS(0, 0);
;   asm volatile("s_waitcnt vmcnt(0)" ::: "memory");
;   __syncthreads();
; template <int EPI, int MI>
; DI void gemm_phase(const GemmDesc& g, char* smem, int vb, int nvb) {
;     ...
;   for (int q = start; q < local; q += step) {
;     const int mg = q / per;
;     const int rem = q - mg * per;
;     const int tn = rem / PM;
;     const int tm = mbase + mg * PM + (rem - tn * PM);
.LBB0_1491:
	s_abs_i32 s0, s40
	v_readlane_b32 s1, v219, 48
	s_mul_hi_u32 s1, s0, s1
	v_readlane_b32 s17, v219, 47
	s_mul_i32 s4, s1, s17
	s_sub_i32 s0, s0, s4
	s_ashr_i32 s15, s40, 31
	s_add_i32 s4, s1, 1
	s_sub_i32 s5, s0, s17
	s_cmp_ge_u32 s0, s17
	s_cselect_b32 s1, s4, s1
	s_cselect_b32 s0, s5, s0
	s_add_i32 s4, s1, 1
	s_cmp_ge_u32 s0, s17
	s_cselect_b32 s0, s4, s1
	s_xor_b32 s16, s0, s15
	s_sub_i32 s0, s16, s15
	s_mul_i32 s1, s0, s17
	s_sub_i32 s1, s40, s1
	s_abs_i32 s4, s1
	v_readlane_b32 s5, v219, 46
	s_mul_hi_u32 s5, s4, s5
	v_readlane_b32 s41, v218, 32
	s_mul_i32 s18, s5, s41
	s_sub_i32 s4, s4, s18
	s_ashr_i32 s17, s1, 31
	s_add_i32 s18, s5, 1
	s_sub_i32 s19, s4, s41
	s_cmp_ge_u32 s4, s41
	s_cselect_b32 s5, s18, s5
	s_cselect_b32 s4, s19, s4
	s_add_i32 s18, s5, 1
	s_cmp_ge_u32 s4, s41
	s_cselect_b32 s4, s18, s5
	s_xor_b32 s18, s4, s17
	v_mov_b32_e32 v97, v132
	s_sub_i32 s4, s18, s17
	s_mul_i32 s0, s0, s41
	v_ashrrev_i32_e32 v6, 3, v97
	s_mul_i32 s5, s4, s41
	s_waitcnt vmcnt(8)
	v_ashrrev_i32_e32 v109, 7, v97
	v_bfe_u32 v1, v97, 6, 2
	v_xor_b32_e32 v2, v6, v97
	s_add_i32 s0, s0, s54
	s_sub_i32 s1, s1, s5
	v_and_b32_e32 v108, 31, v97
	v_bitop3_b32 v2, v2, v1, 7 bitop3:0x6c
	v_mul_lo_u32 v1, v109, s6
	s_add_i32 s1, s0, s1
	s_lshl_b32 s0, s4, 7
	v_and_b32_e32 v0, 7, v97
	v_or_b32_e32 v7, v1, v108
	v_lshrrev_b32_e32 v1, 3, v97
	v_readlane_b32 s4, v221, 5
	s_mul_i32 s41, s1, 0xc0
	v_bfe_u32 v115, v97, 5, 1
	v_bitop3_b32 v0, v1, v0, 3 bitop3:0x6c
	v_readlane_b32 s5, v221, 6
	v_xor_b32_e32 v8, v0, v115
	v_add_u32_e32 v3, s41, v6
	v_mov_b64_e32 v[0:1], s[4:5]
	s_movk_i32 s19, 0x1600
	v_mad_i64_i32 v[0:1], s[4:5], v3, s19, v[0:1]
	v_readlane_b32 s4, v220, 56
	v_readlane_b32 s5, v220, 57
	v_lshlrev_b32_e32 v98, 4, v2
	v_add_u32_e32 v9, s0, v6
	v_mov_b64_e32 v[2:3], s[4:5]
	v_lshlrev_b32_e32 v120, 4, v97
	v_mad_i64_i32 v[2:3], s[4:5], v9, s19, v[2:3]
	v_add_u32_e32 v121, 0, v120
	v_mov_b32_e32 v99, v96
	v_readfirstlane_b32 s4, v121
	v_add_u32_e32 v122, 0x1000, v121
	v_lshl_add_u64 v[0:1], v[0:1], 0, v[98:99]
	s_mov_b32 m0, s4
	s_mov_b64 s[42:43], 0x2c000
	v_readfirstlane_b32 s4, v122
	v_add_u32_e32 v123, 0x2000, v121
	global_load_lds_dwordx4 v[0:1], off
	v_lshl_add_u64 v[4:5], v[0:1], 0, s[42:43]
	s_mov_b32 m0, s4
	s_mov_b64 s[44:45], 0x58000
	v_readfirstlane_b32 s4, v123
	v_add_u32_e32 v124, 0x3000, v121
	global_load_lds_dwordx4 v[4:5], off
	v_lshl_add_u64 v[4:5], v[0:1], 0, s[44:45]
	s_mov_b32 m0, s4
	s_mov_b64 s[46:47], 0x84000
	v_readfirstlane_b32 s4, v124
	global_load_lds_dwordx4 v[4:5], off
	v_lshl_add_u64 v[4:5], v[0:1], 0, s[46:47]
	s_mov_b32 m0, s4
	s_mov_b64 s[4:5], 0xb0000
	v_add_u32_e32 v125, 0x4000, v121
	global_load_lds_dwordx4 v[4:5], off
	v_lshl_add_u64 v[4:5], v[0:1], 0, s[4:5]
	v_readfirstlane_b32 s4, v125
	s_mov_b32 m0, s4
	s_mov_b64 s[4:5], 0xdc000
	v_add_u32_e32 v126, 0x5000, v121
	v_lshl_add_u64 v[0:1], v[0:1], 0, s[4:5]
	v_readfirstlane_b32 s4, v126
	v_add_u32_e32 v127, 0xc000, v121
	global_load_lds_dwordx4 v[4:5], off
	s_mov_b32 m0, s4
	v_readfirstlane_b32 s4, v127
	v_add_u32_e32 v128, 0xd000, v121
	global_load_lds_dwordx4 v[0:1], off
	v_lshl_add_u64 v[0:1], v[2:3], 0, v[98:99]
	s_mov_b32 m0, s4
	v_readfirstlane_b32 s4, v128
	v_add_u32_e32 v129, 0xe000, v121
	global_load_lds_dwordx4 v[0:1], off
	v_lshl_add_u64 v[2:3], v[0:1], 0, s[42:43]
	s_mov_b32 m0, s4
	v_readfirstlane_b32 s4, v129
	v_add_u32_e32 v130, 0xf000, v121
	global_load_lds_dwordx4 v[2:3], off
	v_lshl_add_u64 v[2:3], v[0:1], 0, s[44:45]
	s_mov_b32 m0, s4
	v_readfirstlane_b32 s4, v130
	global_load_lds_dwordx4 v[2:3], off
	v_lshl_add_u64 v[0:1], v[0:1], 0, s[46:47]
	s_mov_b32 m0, s4
	s_mul_i32 s15, s15, 7
	global_load_lds_dwordx4 v[0:1], off
	s_add_i32 s17, s17, s15
	s_sub_i32 s4, s17, s18
	s_mul_i32 s16, s16, 7
	s_sub_i32 s4, s4, s16
	v_readlane_b32 s5, v218, 33
	v_lshlrev_b32_e32 v0, 7, v97
	s_mul_i32 s4, s5, s4
	v_and_b32_e32 v0, 0x2f80, v0
	s_add_i32 s4, s4, s39
	s_waitcnt vmcnt(0)
	v_add_u32_e32 v153, 0, v0
	v_add_u32_e32 v155, s10, v0
	v_add_u32_e32 v2, s4, v6
	v_mov_b64_e32 v[0:1], s[70:71]
	v_lshlrev_b32_e32 v154, 4, v8
	v_mad_i64_i32 v[100:101], s[4:5], v2, s19, v[0:1]
	v_mad_i64_i32 v[102:103], s[4:5], v9, s19, v[0:1]
	v_mov_b32_e32 v0, 0
	v_lshl_add_u32 v131, v7, 7, 0
	v_xor_b32_e32 v156, 32, v154
	v_xor_b32_e32 v157, 64, v154
	v_xor_b32_e32 v158, 0x60, v154
	s_mov_b32 s15, 0
	v_mov_b32_e32 v1, v0
	v_mov_b32_e32 v2, v0
	v_mov_b32_e32 v3, v0
	v_mov_b32_e32 v4, v0
	v_mov_b32_e32 v5, v0
	v_mov_b32_e32 v6, v0
	v_mov_b32_e32 v7, v0
	v_mov_b32_e32 v8, v0
	v_mov_b32_e32 v9, v0
	v_mov_b32_e32 v10, v0
	v_mov_b32_e32 v11, v0
	v_mov_b32_e32 v12, v0
	v_mov_b32_e32 v13, v0
	v_mov_b32_e32 v14, v0
	v_mov_b32_e32 v15, v0
	v_mov_b32_e32 v16, v0
	v_mov_b32_e32 v17, v0
	v_mov_b32_e32 v18, v0
	v_mov_b32_e32 v19, v0
	v_mov_b32_e32 v20, v0
	v_mov_b32_e32 v21, v0
	v_mov_b32_e32 v22, v0
	v_mov_b32_e32 v23, v0
	v_mov_b32_e32 v24, v0
	v_mov_b32_e32 v25, v0
	v_mov_b32_e32 v26, v0
	v_mov_b32_e32 v27, v0
	v_mov_b32_e32 v28, v0
	v_mov_b32_e32 v29, v0
	v_mov_b32_e32 v30, v0
	v_mov_b32_e32 v31, v0
	v_mov_b32_e32 v32, v0
	v_mov_b32_e32 v33, v0
	v_mov_b32_e32 v34, v0
	v_mov_b32_e32 v35, v0
	v_mov_b32_e32 v36, v0
	v_mov_b32_e32 v37, v0
	v_mov_b32_e32 v38, v0
	v_mov_b32_e32 v39, v0
	v_mov_b32_e32 v40, v0
	v_mov_b32_e32 v41, v0
	v_mov_b32_e32 v42, v0
	v_mov_b32_e32 v43, v0
	v_mov_b32_e32 v44, v0
	v_mov_b32_e32 v45, v0
	v_mov_b32_e32 v46, v0
	v_mov_b32_e32 v47, v0
	v_mov_b32_e32 v48, v0
	s_waitcnt vmcnt(0)
; template <int EPI, int MI>
; DI void gemm_tile(const GemmDesc& g, int tm, int tn, char* smem) {
;     ...
; #pragma unroll
;   for (int a = 0; a < MI; ++a)
; #pragma unroll
;     for (int b = 0; b < 2; ++b)
; #pragma unroll
;       for (int i = 0; i < 16; ++i) acc[a][b][i] = 0.f;
;   const int srow = tid >> 3;
;   const int schunk = (tid & 7) ^ ((srow & 7) ^ ((srow >> 3) & 3));
;     ...
;   const int rowA = wm * (32 * MI) + r, rowB = wn * 64 + r;
;   const int hk = hh ^ ((r & 7) ^ ((r >> 3) & 3));
;     ...
;   G_GLDS(0, 0);
;   asm volatile("s_waitcnt vmcnt(0)" ::: "memory");
;   __syncthreads();
;   for (int kt = 0; kt < nk; kt += 2) {
;     if (kt + 1 < nk) G_GLDS(kt + 1, 1);
;     G_COMPUTE(0);
;     asm volatile("s_waitcnt vmcnt(0)" ::: "memory");
;     __syncthreads();
	v_mov_b32_e32 v49, v0
	v_mov_b32_e32 v50, v0
	v_mov_b32_e32 v51, v0
	v_mov_b32_e32 v52, v0
	v_mov_b32_e32 v53, v0
	v_mov_b32_e32 v54, v0
	v_mov_b32_e32 v55, v0
	v_mov_b32_e32 v56, v0
	v_mov_b32_e32 v57, v0
	v_mov_b32_e32 v58, v0
	v_mov_b32_e32 v59, v0
	v_mov_b32_e32 v60, v0
	v_mov_b32_e32 v61, v0
	v_mov_b32_e32 v62, v0
	v_mov_b32_e32 v63, v0
	v_mov_b32_e32 v64, v0
	v_mov_b32_e32 v65, v0
	v_mov_b32_e32 v66, v0
	v_mov_b32_e32 v67, v0
	v_mov_b32_e32 v68, v0
	v_mov_b32_e32 v69, v0
	v_mov_b32_e32 v70, v0
	v_mov_b32_e32 v71, v0
	v_mov_b32_e32 v72, v0
	v_mov_b32_e32 v73, v0
	v_mov_b32_e32 v74, v0
	v_mov_b32_e32 v75, v0
	v_mov_b32_e32 v76, v0
	v_mov_b32_e32 v77, v0
	v_mov_b32_e32 v78, v0
	v_mov_b32_e32 v79, v0
	v_mov_b32_e32 v80, v0
	v_mov_b32_e32 v81, v0
	v_mov_b32_e32 v82, v0
	v_mov_b32_e32 v83, v0
	v_mov_b32_e32 v84, v0
	v_mov_b32_e32 v85, v0
	v_mov_b32_e32 v86, v0
	v_mov_b32_e32 v87, v0
	v_mov_b32_e32 v88, v0
	v_mov_b32_e32 v89, v0
	v_mov_b32_e32 v90, v0
	v_mov_b32_e32 v91, v0
	v_mov_b32_e32 v92, v0
	v_mov_b32_e32 v93, v0
	v_mov_b32_e32 v94, v0
	v_mov_b32_e32 v95, v0
	v_add_u32_e32 v162, v131, v154
	v_add_u32_e32 v163, v131, v156
	v_add_u32_e32 v164, v131, v157
	v_add_u32_e32 v165, v131, v158
	v_add_u32_e32 v166, v153, v154
	v_add_u32_e32 v167, v153, v156
	v_add_u32_e32 v168, v153, v157
	v_add_u32_e32 v169, v153, v158
	v_add_u32_e32 v170, v155, v154
	v_add_u32_e32 v171, v155, v156
	v_add_u32_e32 v172, v155, v157
	v_add_u32_e32 v173, v155, v158
	v_lshl_add_u64 v[252:253], v[100:101], 0, v[98:99]
	v_lshl_add_u64 v[254:255], v[102:103], 0, v[98:99]
	v_readfirstlane_b32 s100, v121
	s_mov_b64 s[4:5], 0x80
	s_waitcnt vmcnt(0) lgkmcnt(0)
	s_barrier
	s_mov_b64 s[16:17], 0x5872080
	s_add_u32 m0, s100, 0x6000
	v_lshl_add_u64 v[106:107], v[252:253], 0, s[16:17]
	global_load_lds_dwordx4 v[106:107], off
	s_mov_b64 s[16:17], 0x589e080
	s_add_u32 m0, s100, 0x7000
	v_lshl_add_u64 v[106:107], v[252:253], 0, s[16:17]
	global_load_lds_dwordx4 v[106:107], off
	s_mov_b64 s[16:17], 0x58ca080
	s_add_u32 m0, s100, 0x8000
	v_lshl_add_u64 v[106:107], v[252:253], 0, s[16:17]
	global_load_lds_dwordx4 v[106:107], off
	s_mov_b64 s[16:17], 0x58f6080
	s_add_u32 m0, s100, 0x9000
	v_lshl_add_u64 v[106:107], v[252:253], 0, s[16:17]
	global_load_lds_dwordx4 v[106:107], off
	s_mov_b64 s[16:17], 0x5922080
	s_add_u32 m0, s100, 0xa000
	v_lshl_add_u64 v[106:107], v[252:253], 0, s[16:17]
	global_load_lds_dwordx4 v[106:107], off
	s_mov_b64 s[16:17], 0x594e080
	s_add_u32 m0, s100, 0xb000
	v_lshl_add_u64 v[106:107], v[252:253], 0, s[16:17]
	global_load_lds_dwordx4 v[106:107], off
	v_lshl_add_u64 v[252:253], v[252:253], 0, s[4:5]
	s_mov_b64 s[16:17], 0x1b80080
	s_add_u32 m0, s100, 0x10000
	v_lshl_add_u64 v[106:107], v[254:255], 0, s[16:17]
	global_load_lds_dwordx4 v[106:107], off
	s_mov_b64 s[16:17], 0x1bac080
	s_add_u32 m0, s100, 0x11000
	v_lshl_add_u64 v[106:107], v[254:255], 0, s[16:17]
	global_load_lds_dwordx4 v[106:107], off
	s_mov_b64 s[16:17], 0x1bd8080
	s_add_u32 m0, s100, 0x12000
	v_lshl_add_u64 v[106:107], v[254:255], 0, s[16:17]
	global_load_lds_dwordx4 v[106:107], off
	s_mov_b64 s[16:17], 0x1c04080
	s_add_u32 m0, s100, 0x13000
	v_lshl_add_u64 v[106:107], v[254:255], 0, s[16:17]
	global_load_lds_dwordx4 v[106:107], off
	v_lshl_add_u64 v[254:255], v[254:255], 0, s[4:5]
	ds_read_b128 v[236:239], v166 offset:49152
	ds_read_b128 v[240:243], v166 offset:53248
	ds_read_b128 v[224:227], v162
	ds_read_b128 v[228:231], v162 offset:4096
	s_mov_b32 s15, 0
.Lge_loop:
	ds_read_b128 v[232:235], v162 offset:8192
	s_waitcnt lgkmcnt(2)
	v_mfma_f32_32x32x16_bf16 v[80:95], v[224:227], v[236:239], v[80:95]
	v_mfma_f32_32x32x16_bf16 v[64:79], v[224:227], v[240:243], v[64:79]
	ds_read_b128 v[244:247], v167 offset:49152
	ds_read_b128 v[248:251], v167 offset:53248
	ds_read_b128 v[224:227], v163
	s_waitcnt lgkmcnt(4)
	v_mfma_f32_32x32x16_bf16 v[48:63], v[228:231], v[236:239], v[48:63]
	v_mfma_f32_32x32x16_bf16 v[32:47], v[228:231], v[240:243], v[32:47]
	ds_read_b128 v[228:231], v163 offset:4096
	s_waitcnt lgkmcnt(4)
	v_mfma_f32_32x32x16_bf16 v[16:31], v[232:235], v[236:239], v[16:31]
	v_mfma_f32_32x32x16_bf16 v[0:15], v[232:235], v[240:243], v[0:15]
	ds_read_b128 v[232:235], v163 offset:8192
	s_waitcnt lgkmcnt(2)
	v_mfma_f32_32x32x16_bf16 v[80:95], v[224:227], v[244:247], v[80:95]
	v_mfma_f32_32x32x16_bf16 v[64:79], v[224:227], v[248:251], v[64:79]
	ds_read_b128 v[236:239], v168 offset:49152
	ds_read_b128 v[240:243], v168 offset:53248
	ds_read_b128 v[224:227], v164
	s_waitcnt lgkmcnt(4)
	v_mfma_f32_32x32x16_bf16 v[48:63], v[228:231], v[244:247], v[48:63]
	v_mfma_f32_32x32x16_bf16 v[32:47], v[228:231], v[248:251], v[32:47]
	ds_read_b128 v[228:231], v164 offset:4096
	s_waitcnt lgkmcnt(4)
	v_mfma_f32_32x32x16_bf16 v[16:31], v[232:235], v[244:247], v[16:31]
	v_mfma_f32_32x32x16_bf16 v[0:15], v[232:235], v[248:251], v[0:15]
	ds_read_b128 v[232:235], v164 offset:8192
	s_waitcnt lgkmcnt(2)
	v_mfma_f32_32x32x16_bf16 v[80:95], v[224:227], v[236:239], v[80:95]
	v_mfma_f32_32x32x16_bf16 v[64:79], v[224:227], v[240:243], v[64:79]
	ds_read_b128 v[244:247], v169 offset:49152
	ds_read_b128 v[248:251], v169 offset:53248
	ds_read_b128 v[224:227], v165
	s_waitcnt lgkmcnt(4)
	v_mfma_f32_32x32x16_bf16 v[48:63], v[228:231], v[236:239], v[48:63]
	v_mfma_f32_32x32x16_bf16 v[32:47], v[228:231], v[240:243], v[32:47]
	ds_read_b128 v[228:231], v165 offset:4096
	s_waitcnt lgkmcnt(4)
	v_mfma_f32_32x32x16_bf16 v[16:31], v[232:235], v[236:239], v[16:31]
	v_mfma_f32_32x32x16_bf16 v[0:15], v[232:235], v[240:243], v[0:15]
	ds_read_b128 v[232:235], v165 offset:8192
	s_waitcnt lgkmcnt(2)
	v_mfma_f32_32x32x16_bf16 v[80:95], v[224:227], v[244:247], v[80:95]
	v_mfma_f32_32x32x16_bf16 v[64:79], v[224:227], v[248:251], v[64:79]
	s_waitcnt lgkmcnt(0)
	s_waitcnt vmcnt(0)
	s_barrier
; template <int EPI, int MI>
; DI void gemm_tile(const GemmDesc& g, int tm, int tn, char* smem) {
;     ...
;   const int rowA = wm * (32 * MI) + r, rowB = wn * 64 + r;
;   const int hk = hh ^ ((r & 7) ^ ((r >> 3) & 3));
;     ...
;   G_GLDS(0, 0);
;   asm volatile("s_waitcnt vmcnt(0)" ::: "memory");
;   __syncthreads();
;   for (int kt = 0; kt < nk; kt += 2) {
;     if (kt + 1 < nk) G_GLDS(kt + 1, 1);
;     G_COMPUTE(0);
;     asm volatile("s_waitcnt vmcnt(0)" ::: "memory");
;     __syncthreads();
;     if (kt + 1 < nk) {
;       if (kt + 2 < nk) G_GLDS(kt + 2, 0);
;       G_COMPUTE(1);
;       asm volatile("s_waitcnt vmcnt(0)" ::: "memory");
;       __syncthreads();
;     }
	s_cmp_eq_u32 s15, 42
	s_cbranch_scc1 .Lge_noearly
	s_mov_b64 s[16:17], 0x5872080
	s_mov_b32 m0, s100
	v_lshl_add_u64 v[106:107], v[252:253], 0, s[16:17]
	global_load_lds_dwordx4 v[106:107], off
	s_mov_b64 s[16:17], 0x589e080
	s_add_u32 m0, s100, 0x1000
	v_lshl_add_u64 v[106:107], v[252:253], 0, s[16:17]
	global_load_lds_dwordx4 v[106:107], off
	s_mov_b64 s[16:17], 0x58ca080
	s_add_u32 m0, s100, 0x2000
	v_lshl_add_u64 v[106:107], v[252:253], 0, s[16:17]
	global_load_lds_dwordx4 v[106:107], off
	s_mov_b64 s[16:17], 0x58f6080
	s_add_u32 m0, s100, 0x3000
	v_lshl_add_u64 v[106:107], v[252:253], 0, s[16:17]
	global_load_lds_dwordx4 v[106:107], off
	s_mov_b64 s[16:17], 0x5922080
	s_add_u32 m0, s100, 0x4000
	v_lshl_add_u64 v[106:107], v[252:253], 0, s[16:17]
	global_load_lds_dwordx4 v[106:107], off
	s_mov_b64 s[16:17], 0x594e080
	s_add_u32 m0, s100, 0x5000
	v_lshl_add_u64 v[106:107], v[252:253], 0, s[16:17]
	global_load_lds_dwordx4 v[106:107], off
	v_lshl_add_u64 v[252:253], v[252:253], 0, s[4:5]
	s_mov_b64 s[16:17], 0x1b80080
	s_add_u32 m0, s100, 0xc000
	v_lshl_add_u64 v[106:107], v[254:255], 0, s[16:17]
	global_load_lds_dwordx4 v[106:107], off
	s_mov_b64 s[16:17], 0x1bac080
	s_add_u32 m0, s100, 0xd000
	v_lshl_add_u64 v[106:107], v[254:255], 0, s[16:17]
	global_load_lds_dwordx4 v[106:107], off
	s_mov_b64 s[16:17], 0x1bd8080
	s_add_u32 m0, s100, 0xe000
	v_lshl_add_u64 v[106:107], v[254:255], 0, s[16:17]
	global_load_lds_dwordx4 v[106:107], off
	s_mov_b64 s[16:17], 0x1c04080
	s_add_u32 m0, s100, 0xf000
	v_lshl_add_u64 v[106:107], v[254:255], 0, s[16:17]
	global_load_lds_dwordx4 v[106:107], off
	v_lshl_add_u64 v[254:255], v[254:255], 0, s[4:5]
.Lge_noearly:
	ds_read_b128 v[236:239], v170
	ds_read_b128 v[240:243], v170 offset:4096
	ds_read_b128 v[224:227], v162 offset:24576
	v_mfma_f32_32x32x16_bf16 v[48:63], v[228:231], v[244:247], v[48:63]
	v_mfma_f32_32x32x16_bf16 v[32:47], v[228:231], v[248:251], v[32:47]
	ds_read_b128 v[228:231], v162 offset:28672
	v_mfma_f32_32x32x16_bf16 v[16:31], v[232:235], v[244:247], v[16:31]
	v_mfma_f32_32x32x16_bf16 v[0:15], v[232:235], v[248:251], v[0:15]
	s_cmp_eq_u32 s15, 42
	s_cbranch_scc1 .Lge_last
	ds_read_b128 v[232:235], v162 offset:32768
	s_waitcnt lgkmcnt(2)
	v_mfma_f32_32x32x16_bf16 v[80:95], v[224:227], v[236:239], v[80:95]
	v_mfma_f32_32x32x16_bf16 v[64:79], v[224:227], v[240:243], v[64:79]
	ds_read_b128 v[244:247], v171
	ds_read_b128 v[248:251], v171 offset:4096
	ds_read_b128 v[224:227], v163 offset:24576
	s_waitcnt lgkmcnt(4)
	v_mfma_f32_32x32x16_bf16 v[48:63], v[228:231], v[236:239], v[48:63]
	v_mfma_f32_32x32x16_bf16 v[32:47], v[228:231], v[240:243], v[32:47]
	ds_read_b128 v[228:231], v163 offset:28672
	s_waitcnt lgkmcnt(4)
	v_mfma_f32_32x32x16_bf16 v[16:31], v[232:235], v[236:239], v[16:31]
	v_mfma_f32_32x32x16_bf16 v[0:15], v[232:235], v[240:243], v[0:15]
	ds_read_b128 v[232:235], v163 offset:32768
	s_waitcnt lgkmcnt(2)
	v_mfma_f32_32x32x16_bf16 v[80:95], v[224:227], v[244:247], v[80:95]
	v_mfma_f32_32x32x16_bf16 v[64:79], v[224:227], v[248:251], v[64:79]
	ds_read_b128 v[236:239], v172
	ds_read_b128 v[240:243], v172 offset:4096
	ds_read_b128 v[224:227], v164 offset:24576
	s_waitcnt lgkmcnt(4)
	v_mfma_f32_32x32x16_bf16 v[48:63], v[228:231], v[244:247], v[48:63]
	v_mfma_f32_32x32x16_bf16 v[32:47], v[228:231], v[248:251], v[32:47]
	ds_read_b128 v[228:231], v164 offset:28672
	s_waitcnt lgkmcnt(4)
	v_mfma_f32_32x32x16_bf16 v[16:31], v[232:235], v[244:247], v[16:31]
	v_mfma_f32_32x32x16_bf16 v[0:15], v[232:235], v[248:251], v[0:15]
	ds_read_b128 v[232:235], v164 offset:32768
	s_waitcnt lgkmcnt(2)
	v_mfma_f32_32x32x16_bf16 v[80:95], v[224:227], v[236:239], v[80:95]
	v_mfma_f32_32x32x16_bf16 v[64:79], v[224:227], v[240:243], v[64:79]
	ds_read_b128 v[244:247], v173
	ds_read_b128 v[248:251], v173 offset:4096
	ds_read_b128 v[224:227], v165 offset:24576
	s_waitcnt lgkmcnt(4)
	v_mfma_f32_32x32x16_bf16 v[48:63], v[228:231], v[236:239], v[48:63]
	v_mfma_f32_32x32x16_bf16 v[32:47], v[228:231], v[240:243], v[32:47]
	ds_read_b128 v[228:231], v165 offset:28672
	s_waitcnt lgkmcnt(4)
	v_mfma_f32_32x32x16_bf16 v[16:31], v[232:235], v[236:239], v[16:31]
	v_mfma_f32_32x32x16_bf16 v[0:15], v[232:235], v[240:243], v[0:15]
	ds_read_b128 v[232:235], v165 offset:32768
	s_waitcnt lgkmcnt(2)
	v_mfma_f32_32x32x16_bf16 v[80:95], v[224:227], v[244:247], v[80:95]
	v_mfma_f32_32x32x16_bf16 v[64:79], v[224:227], v[248:251], v[64:79]
	s_waitcnt lgkmcnt(0)
	s_waitcnt vmcnt(0)
	s_barrier
	s_mov_b64 s[16:17], 0x5872080
	s_add_u32 m0, s100, 0x6000
	v_lshl_add_u64 v[106:107], v[252:253], 0, s[16:17]
	global_load_lds_dwordx4 v[106:107], off
	s_mov_b64 s[16:17], 0x589e080
	s_add_u32 m0, s100, 0x7000
	v_lshl_add_u64 v[106:107], v[252:253], 0, s[16:17]
	global_load_lds_dwordx4 v[106:107], off
	s_mov_b64 s[16:17], 0x58ca080
	s_add_u32 m0, s100, 0x8000
	v_lshl_add_u64 v[106:107], v[252:253], 0, s[16:17]
	global_load_lds_dwordx4 v[106:107], off
	s_mov_b64 s[16:17], 0x58f6080
	s_add_u32 m0, s100, 0x9000
	v_lshl_add_u64 v[106:107], v[252:253], 0, s[16:17]
	global_load_lds_dwordx4 v[106:107], off
	s_mov_b64 s[16:17], 0x5922080
	s_add_u32 m0, s100, 0xa000
	v_lshl_add_u64 v[106:107], v[252:253], 0, s[16:17]
	global_load_lds_dwordx4 v[106:107], off
	s_mov_b64 s[16:17], 0x594e080
	s_add_u32 m0, s100, 0xb000
	v_lshl_add_u64 v[106:107], v[252:253], 0, s[16:17]
	global_load_lds_dwordx4 v[106:107], off
	v_lshl_add_u64 v[252:253], v[252:253], 0, s[4:5]
	s_mov_b64 s[16:17], 0x1b80080
	s_add_u32 m0, s100, 0x10000
	v_lshl_add_u64 v[106:107], v[254:255], 0, s[16:17]
	global_load_lds_dwordx4 v[106:107], off
	s_mov_b64 s[16:17], 0x1bac080
	s_add_u32 m0, s100, 0x11000
	v_lshl_add_u64 v[106:107], v[254:255], 0, s[16:17]
	global_load_lds_dwordx4 v[106:107], off
	s_mov_b64 s[16:17], 0x1bd8080
	s_add_u32 m0, s100, 0x12000
	v_lshl_add_u64 v[106:107], v[254:255], 0, s[16:17]
	global_load_lds_dwordx4 v[106:107], off
	s_mov_b64 s[16:17], 0x1c04080
	s_add_u32 m0, s100, 0x13000
	v_lshl_add_u64 v[106:107], v[254:255], 0, s[16:17]
	global_load_lds_dwordx4 v[106:107], off
	v_lshl_add_u64 v[254:255], v[254:255], 0, s[4:5]
	ds_read_b128 v[236:239], v166 offset:49152
	ds_read_b128 v[240:243], v166 offset:53248
	ds_read_b128 v[224:227], v162
	v_mfma_f32_32x32x16_bf16 v[48:63], v[228:231], v[244:247], v[48:63]
	v_mfma_f32_32x32x16_bf16 v[32:47], v[228:231], v[248:251], v[32:47]
	ds_read_b128 v[228:231], v162 offset:4096
	v_mfma_f32_32x32x16_bf16 v[16:31], v[232:235], v[244:247], v[16:31]
	v_mfma_f32_32x32x16_bf16 v[0:15], v[232:235], v[248:251], v[0:15]
	s_add_u32 s15, s15, 2
	s_branch .Lge_loop
